# row-norm rebalance v2: sample rows spread one per workgroup over 128 workgroups (was 8 per WG on 16), orphan rows to 256 other waves
# speedup vs baseline: 1.0119x; 1.0119x over previous
.LBB0_1005:
	v_readlane_b32 s2, v248, 0
	v_readlane_b32 s3, v248, 1
	s_cmp_lt_i32 s2, 8
	s_cselect_b64 s[2:3], -1, 0
	s_and_b64 s[2:3], s[2:3], s[0:1]
	s_andn2_b64 vcc, exec, s[2:3]
	s_cbranch_vccnz .LBB0_1019
	v_lshl_or_b32 v34, s82, 3, v210
	s_movk_i32 s0, 0x4080
	v_cmp_gt_i32_e32 vcc, s0, v34
	s_and_saveexec_b64 s[4:5], vcc
	s_cbranch_execz .LBB0_1018
	v_lshlrev_b32_e32 v1, 2, v0
	v_and_b32_e32 v18, 0xfc, v1
	v_lshlrev_b32_e32 v36, 2, v18
	global_load_dwordx4 v[2:5], v36, s[80:81]
	global_load_dwordx4 v[6:9], v36, s[80:81] offset:1024
	global_load_dwordx4 v[10:13], v36, s[80:81] offset:2048
	global_load_dwordx4 v[14:17], v36, s[80:81] offset:3072
	v_mbcnt_lo_u32_b32 v1, -1, 0
	v_mbcnt_hi_u32_b32 v19, -1, v1
	v_and_b32_e32 v22, 64, v19
	v_xor_b32_e32 v1, 1, v19
	v_add_u32_e32 v22, 64, v22
	v_cmp_lt_i32_e32 vcc, v1, v22
	v_xor_b32_e32 v23, 2, v19
	v_readlane_b32 s8, v248, 2
	v_cndmask_b32_e32 v1, v19, v1, vcc
	v_cmp_lt_i32_e32 vcc, v23, v22
	v_mov_b32_e32 v37, 0
	v_readlane_b32 s9, v248, 3
	v_cndmask_b32_e32 v23, v19, v23, vcc
	v_lshlrev_b32_e32 v46, 2, v23
	v_xor_b32_e32 v23, 4, v19
	v_cmp_lt_i32_e32 vcc, v23, v22
	v_readlane_b32 s10, v248, 4
	v_readlane_b32 s11, v248, 5
	v_cndmask_b32_e32 v23, v19, v23, vcc
	v_lshlrev_b32_e32 v47, 2, v23
	v_xor_b32_e32 v23, 8, v19
	v_cmp_lt_i32_e32 vcc, v23, v22
	s_cmp_lg_u64 s[10:11], 0
	v_lshl_add_u64 v[20:21], s[94:95], 0, v[36:37]
	v_cndmask_b32_e32 v23, v19, v23, vcc
	v_lshlrev_b32_e32 v48, 2, v23
	v_xor_b32_e32 v23, 16, v19
	v_cmp_lt_i32_e32 vcc, v23, v22
	s_mov_b64 s[8:9], 0xb3d6400
	v_lshl_add_u64 v[40:41], s[92:93], 0, v[36:37]
	v_cndmask_b32_e32 v23, v19, v23, vcc
	v_lshlrev_b32_e32 v49, 2, v23
	v_xor_b32_e32 v23, 32, v19
	v_lshlrev_b32_e32 v36, 1, v18
	v_cmp_lt_i32_e32 vcc, v23, v22
	s_cselect_b64 s[0:1], -1, 0
	v_lshl_add_u64 v[38:39], v[20:21], 0, s[8:9]
	v_lshl_add_u64 v[20:21], s[94:95], 0, v[36:37]
	s_mov_b64 s[8:9], 0xbf0cc00
	v_cndmask_b32_e32 v19, v19, v23, vcc
	v_readlane_b32 s12, v248, 6
	v_readlane_b32 s13, v248, 7
	v_readlane_b32 s14, v248, 8
	v_readlane_b32 s15, v248, 9
	v_readlane_b32 s16, v248, 10
	v_readlane_b32 s17, v248, 11
	v_readlane_b32 s18, v248, 12
	v_readlane_b32 s19, v248, 13
	v_readlane_b32 s20, v248, 14
	v_readlane_b32 s21, v248, 15
	v_readlane_b32 s22, v248, 16
	v_lshl_add_u64 v[42:43], v[20:21], 0, s[8:9]
	v_lshlrev_b32_e32 v50, 2, v19
	s_mov_b64 s[8:9], 0x1f80000
	v_cndmask_b32_e64 v19, 0, 1, s[0:1]
	s_mov_b64 s[6:7], 0
	v_lshlrev_b32_e32 v1, 2, v1
	v_lshl_add_u64 v[44:45], v[20:21], 0, s[8:9]
	s_waitcnt lgkmcnt(0)
	s_lshl_b32 s12, s96, 3
	s_movk_i32 s13, 0x3fff
	v_cmp_ne_u32_e64 s[0:1], 1, v19
	v_lshlrev_b32_e32 v36, 2, v18
	s_mov_b32 s14, 0x80000
	s_mov_b32 s15, 0x100000
	s_mov_b32 s16, 0x180000
	s_mov_b32 s17, 0x200000
	s_mov_b32 s18, 0x280000
	s_mov_b32 s19, 0x300000
	s_mov_b32 s20, 0x380000
	v_mov_b32_e32 v51, 0x3727c5ac
	s_mov_b32 s21, 0x800000
	s_movk_i32 s22, 0x407f
	v_readlane_b32 s23, v248, 17
	v_and_b32_e32 v216, 15, v34
	v_add_u32_e32 v212, 0x4000, v34
	v_mov_b32_e32 v213, 0x7fffffff
	v_mov_b32_e32 v214, -1
	v_mov_b32_e32 v215, 0x7fffffff
	v_add_u32_e32 v217, 0x3000, v34
	v_lshrrev_b32_e32 v218, 4, v34
	v_add_u32_e32 v218, 0x4000, v218
	v_cmp_eq_u32_e32 vcc, 0, v216
	s_nop 1
	v_cndmask_b32_e32 v212, v212, v217, vcc
	v_cndmask_b32_e32 v213, v213, v218, vcc
	v_add_u32_e32 v217, 0x2ff8, v34
	v_add_u32_e32 v218, 0x800, v217
	v_cmp_eq_u32_e32 vcc, 8, v216
	s_nop 1
	v_cndmask_b32_e32 v213, v213, v217, vcc
	v_cndmask_b32_e32 v214, v214, v218, vcc
	v_add_u32_e32 v217, 0x37fc, v34
	v_add_u32_e32 v218, 0x800, v217
	v_cmp_eq_u32_e32 vcc, 4, v216
	s_nop 1
	v_cndmask_b32_e32 v213, v213, v217, vcc
	v_cndmask_b32_e32 v214, v214, v218, vcc
	s_branch .LBB0_1009

.LBB0_1262:
	v_readlane_b32 s2, v248, 0
	v_readlane_b32 s3, v248, 1
	s_cmp_lt_i32 s2, 12
	s_cselect_b64 s[2:3], -1, 0
	s_and_b64 s[0:1], s[2:3], s[0:1]
	s_andn2_b64 vcc, exec, s[0:1]
	s_cbranch_vccnz .LBB0_1270
	v_lshl_or_b32 v16, s82, 3, v210
	s_movk_i32 s0, 0x4080
	v_cmp_gt_i32_e32 vcc, s0, v16
	s_and_saveexec_b64 s[0:1], vcc
	s_cbranch_execz .LBB0_1270
	v_lshlrev_b32_e32 v0, 2, v0
	v_and_b32_e32 v17, 0xfc, v0
	v_lshlrev_b32_e32 v18, 2, v17
	global_load_dwordx4 v[0:3], v18, s[90:91]
	global_load_dwordx4 v[4:7], v18, s[90:91] offset:1024
	global_load_dwordx4 v[8:11], v18, s[90:91] offset:2048
	global_load_dwordx4 v[12:15], v18, s[90:91] offset:3072
	v_lshlrev_b32_e32 v22, 1, v17
	v_mbcnt_lo_u32_b32 v17, -1, 0
	v_mbcnt_hi_u32_b32 v17, -1, v17
	v_and_b32_e32 v25, 64, v17
	v_xor_b32_e32 v24, 1, v17
	v_add_u32_e32 v25, 64, v25
	v_cmp_lt_i32_e32 vcc, v24, v25
	v_mov_b32_e32 v19, 0
	v_lshl_add_u64 v[20:21], s[94:95], 0, v[18:19]
	v_cndmask_b32_e32 v24, v17, v24, vcc
	v_lshlrev_b32_e32 v44, 2, v24
	v_xor_b32_e32 v24, 2, v17
	v_cmp_lt_i32_e32 vcc, v24, v25
	s_mov_b64 s[0:1], 0xb3d6400
	v_mov_b32_e32 v23, v19
	v_cndmask_b32_e32 v24, v17, v24, vcc
	v_lshlrev_b32_e32 v45, 2, v24
	v_xor_b32_e32 v24, 4, v17
	v_cmp_lt_i32_e32 vcc, v24, v25
	v_lshl_add_u64 v[20:21], v[20:21], 0, s[0:1]
	v_lshl_add_u64 v[22:23], s[94:95], 0, v[22:23]
	v_cndmask_b32_e32 v24, v17, v24, vcc
	v_lshlrev_b32_e32 v46, 2, v24
	v_xor_b32_e32 v24, 8, v17
	v_cmp_lt_i32_e32 vcc, v24, v25
	s_mov_b64 s[0:1], 0x1f80000
	v_lshl_add_u64 v[22:23], v[22:23], 0, s[0:1]
	v_cndmask_b32_e32 v24, v17, v24, vcc
	v_lshlrev_b32_e32 v47, 2, v24
	v_xor_b32_e32 v24, 16, v17
	v_cmp_lt_i32_e32 vcc, v24, v25
	s_waitcnt lgkmcnt(0)
	s_lshl_b32 s4, s96, 3
	s_mov_b64 s[0:1], 0
	v_cndmask_b32_e32 v24, v17, v24, vcc
	v_lshlrev_b32_e32 v48, 2, v24
	v_xor_b32_e32 v24, 32, v17
	v_cmp_lt_i32_e32 vcc, v24, v25
	s_movk_i32 s5, 0x3fff
	v_mov_b32_e32 v50, 0x3727c5ac
	v_cndmask_b32_e32 v17, v17, v24, vcc
	v_lshlrev_b32_e32 v49, 2, v17
	v_lshl_add_u64 v[24:25], s[92:93], 0, v[18:19]
	s_mov_b32 s6, 0x800000
	s_movk_i32 s7, 0x407f
	v_and_b32_e32 v232, 15, v16
	v_add_u32_e32 v228, 0x4000, v16
	v_mov_b32_e32 v229, 0x7fffffff
	v_mov_b32_e32 v230, -1
	v_mov_b32_e32 v231, 0x7fffffff
	v_add_u32_e32 v233, 0x3000, v16
	v_lshrrev_b32_e32 v234, 4, v16
	v_add_u32_e32 v234, 0x4000, v234
	v_cmp_eq_u32_e32 vcc, 0, v232
	s_nop 1
	v_cndmask_b32_e32 v228, v228, v233, vcc
	v_cndmask_b32_e32 v229, v229, v234, vcc
	v_add_u32_e32 v233, 0x2ff8, v16
	v_add_u32_e32 v234, 0x800, v233
	v_cmp_eq_u32_e32 vcc, 8, v232
	s_nop 1
	v_cndmask_b32_e32 v229, v229, v233, vcc
	v_cndmask_b32_e32 v230, v230, v234, vcc
	v_add_u32_e32 v233, 0x37fc, v16
	v_add_u32_e32 v234, 0x800, v233
	v_cmp_eq_u32_e32 vcc, 4, v232
	s_nop 1
	v_cndmask_b32_e32 v229, v229, v233, vcc
	v_cndmask_b32_e32 v230, v230, v234, vcc
	s_branch .LBB0_1266
